# v7: SwiGLU epilogue rewritten in hazard-free stages without packed mul/shuffles (same math); otherwise v6
# speedup vs baseline: 1.0338x; 1.0051x over previous
; DI unsigned cvt_pk(float lo, float hi) { unsigned r; asm("v_cvt_pk_bf16_f32 %0, %1, %2" : "=v"(r) : "v"(lo), "v"(hi)); return r; }
; DI float siluf_(float x) { return x * sigmoidf_(x); }
;     __device__ __forceinline__ void operator()(const f32x4 (&acc)[2][2][4][2], const Unit& u, int wr, int wc, int fr, int fq) const {
;         const int row0 = u.pm * BM + wr * 64 + fr, col0 = u.pn * 128 + wc * 32 + 8 * fq;
; #pragma unroll
;         for (int ai = 0; ai < 2; ++ai)
; #pragma unroll
;             for (int m = 0; m < 4; ++m) {
;                 const int row = row0 + ai * HALF + m * 16;
;                 const float rs = rsqrtf(ss[row] * (1.f / DM) + EPS);
;                 float h[8];
; #pragma unroll
;                 for (int n = 0; n < 2; ++n)
; #pragma unroll
;                     for (int j = 0; j < 4; ++j) { const float gg = acc[ai][0][m][n][j] * rs, uu = acc[ai][1][m][n][j] * rs; h[4 * n + j] = siluf_(gg) * uu; }
;                 u32x4 w; w.x = cvt_pk(h[0], h[1]); w.y = cvt_pk(h[2], h[3]); w.z = cvt_pk(h[4], h[5]); w.w = cvt_pk(h[6], h[7]);
;                 *(u32x4*)(H + (size_t)row * DFF + col0) = w;
;             }
.LBB0_297:
	v_lshl_add_u32 v138, s41, 8, v155
	v_ashrrev_i32_e32 v139, 31, v138
	v_lshl_add_u64 v[140:141], v[138:139], 2, s[10:11]
	global_load_dword v139, v[140:141], off
	global_load_dword v162, v[140:141], off offset:64
	global_load_dword v163, v[140:141], off offset:128
	global_load_dword v164, v[140:141], off offset:192
	global_load_dword v165, v[140:141], off offset:512
	global_load_dword v166, v[140:141], off offset:576
	global_load_dword v167, v[140:141], off offset:640
	global_load_dword v168, v[140:141], off offset:704
	s_mov_b32 s15, 0x800000
	v_lshl_or_b32 v142, s40, 7, v157
	v_ashrrev_i32_e32 v143, 31, v142
	v_mov_b64_e32 v[186:187], s[8:9]
	v_lshlrev_b64 v[188:189], 1, v[142:143]
	s_waitcnt vmcnt(0)
	v_fmamk_f32 v180, v139, 0x3a800000, v217
	v_cmp_gt_f32_e32 vcc, s15, v180
	v_mul_f32_e32 v181, 0x4b800000, v180
	s_nop 0
	v_cndmask_b32_e32 v180, v180, v181, vcc
	v_rsq_f32_e32 v180, v180
	v_add_u32_e32 v182, 0, v138
	v_mul_f32_e32 v181, 0x45800000, v180
	v_cndmask_b32_e32 v180, v180, v181, vcc
	v_mul_f32_e32 v124, v124, v180
	v_mul_f32_e32 v120, v120, v180
	v_mul_f32_e32 v125, v125, v180
	v_mul_f32_e32 v121, v121, v180
	v_mul_f32_e32 v126, v126, v180
	v_mul_f32_e32 v122, v122, v180
	v_mul_f32_e32 v127, v127, v180
	v_mul_f32_e32 v123, v123, v180
	v_mul_f32_e32 v116, v116, v180
	v_mul_f32_e32 v112, v112, v180
	v_mul_f32_e32 v117, v117, v180
	v_mul_f32_e32 v113, v113, v180
	v_mul_f32_e32 v118, v118, v180
	v_mul_f32_e32 v114, v114, v180
	v_mul_f32_e32 v119, v119, v180
	v_mul_f32_e32 v115, v115, v180
	v_mul_f32_e32 v172, 0xbfb8aa3b, v124
	v_mul_f32_e32 v173, 0xbfb8aa3b, v125
	v_mul_f32_e32 v174, 0xbfb8aa3b, v126
	v_mul_f32_e32 v175, 0xbfb8aa3b, v127
	v_mul_f32_e32 v176, 0xbfb8aa3b, v116
	v_mul_f32_e32 v177, 0xbfb8aa3b, v117
	v_mul_f32_e32 v178, 0xbfb8aa3b, v118
	v_mul_f32_e32 v179, 0xbfb8aa3b, v119
	v_exp_f32_e32 v172, v172
	v_exp_f32_e32 v173, v173
	v_exp_f32_e32 v174, v174
	v_exp_f32_e32 v175, v175
	v_exp_f32_e32 v176, v176
	v_exp_f32_e32 v177, v177
	v_exp_f32_e32 v178, v178
	v_exp_f32_e32 v179, v179
	v_add_f32_e32 v172, 1.0, v172
	v_add_f32_e32 v173, 1.0, v173
	v_add_f32_e32 v174, 1.0, v174
	v_add_f32_e32 v175, 1.0, v175
	v_add_f32_e32 v176, 1.0, v176
	v_add_f32_e32 v177, 1.0, v177
	v_add_f32_e32 v178, 1.0, v178
	v_add_f32_e32 v179, 1.0, v179
	v_rcp_f32_e32 v172, v172
	v_rcp_f32_e32 v173, v173
	v_rcp_f32_e32 v174, v174
	v_rcp_f32_e32 v175, v175
	v_rcp_f32_e32 v176, v176
	v_rcp_f32_e32 v177, v177
	v_rcp_f32_e32 v178, v178
	v_rcp_f32_e32 v179, v179
	v_mul_f32_e32 v124, v124, v172
	v_mul_f32_e32 v125, v125, v173
	v_mul_f32_e32 v126, v126, v174
	v_mul_f32_e32 v127, v127, v175
	v_mul_f32_e32 v116, v116, v176
	v_mul_f32_e32 v117, v117, v177
	v_mul_f32_e32 v118, v118, v178
	v_mul_f32_e32 v119, v119, v179
	v_mul_f32_e32 v124, v120, v124
	v_mul_f32_e32 v125, v121, v125
	v_mul_f32_e32 v126, v122, v126
	v_mul_f32_e32 v127, v123, v127
	v_mul_f32_e32 v116, v112, v116
	v_mul_f32_e32 v117, v113, v117
	v_mul_f32_e32 v118, v114, v118
	v_mul_f32_e32 v119, v115, v119
	v_mad_i64_i32 v[184:185], s[2:3], v182, s64, v[186:187]
	v_cvt_pk_bf16_f32 v172, v124, v125
	v_cvt_pk_bf16_f32 v173, v126, v127
	v_cvt_pk_bf16_f32 v174, v116, v117
	v_cvt_pk_bf16_f32 v175, v118, v119
	v_lshl_add_u64 v[184:185], v[184:185], 0, v[188:189]
	global_store_dwordx4 v[184:185], v[172:175], off
	v_fmamk_f32 v180, v162, 0x3a800000, v217
	v_cmp_gt_f32_e32 vcc, s15, v180
	v_mul_f32_e32 v181, 0x4b800000, v180
	s_nop 0
	v_cndmask_b32_e32 v180, v180, v181, vcc
	v_rsq_f32_e32 v180, v180
	v_add_u32_e32 v182, 16, v138
	v_mul_f32_e32 v181, 0x45800000, v180
	v_cndmask_b32_e32 v180, v180, v181, vcc
	v_mul_f32_e32 v108, v108, v180
	v_mul_f32_e32 v104, v104, v180
	v_mul_f32_e32 v109, v109, v180
	v_mul_f32_e32 v105, v105, v180
	v_mul_f32_e32 v110, v110, v180
	v_mul_f32_e32 v106, v106, v180
	v_mul_f32_e32 v111, v111, v180
	v_mul_f32_e32 v107, v107, v180
	v_mul_f32_e32 v100, v100, v180
	v_mul_f32_e32 v96, v96, v180
	v_mul_f32_e32 v101, v101, v180
	v_mul_f32_e32 v97, v97, v180
	v_mul_f32_e32 v102, v102, v180
	v_mul_f32_e32 v98, v98, v180
	v_mul_f32_e32 v103, v103, v180
	v_mul_f32_e32 v99, v99, v180
	v_mul_f32_e32 v172, 0xbfb8aa3b, v108
	v_mul_f32_e32 v173, 0xbfb8aa3b, v109
	v_mul_f32_e32 v174, 0xbfb8aa3b, v110
	v_mul_f32_e32 v175, 0xbfb8aa3b, v111
	v_mul_f32_e32 v176, 0xbfb8aa3b, v100
	v_mul_f32_e32 v177, 0xbfb8aa3b, v101
	v_mul_f32_e32 v178, 0xbfb8aa3b, v102
	v_mul_f32_e32 v179, 0xbfb8aa3b, v103
	v_exp_f32_e32 v172, v172
	v_exp_f32_e32 v173, v173
	v_exp_f32_e32 v174, v174
	v_exp_f32_e32 v175, v175
	v_exp_f32_e32 v176, v176
	v_exp_f32_e32 v177, v177
	v_exp_f32_e32 v178, v178
	v_exp_f32_e32 v179, v179
	v_add_f32_e32 v172, 1.0, v172
	v_add_f32_e32 v173, 1.0, v173
	v_add_f32_e32 v174, 1.0, v174
	v_add_f32_e32 v175, 1.0, v175
	v_add_f32_e32 v176, 1.0, v176
	v_add_f32_e32 v177, 1.0, v177
	v_add_f32_e32 v178, 1.0, v178
	v_add_f32_e32 v179, 1.0, v179
	v_rcp_f32_e32 v172, v172
	v_rcp_f32_e32 v173, v173
	v_rcp_f32_e32 v174, v174
	v_rcp_f32_e32 v175, v175
	v_rcp_f32_e32 v176, v176
	v_rcp_f32_e32 v177, v177
	v_rcp_f32_e32 v178, v178
	v_rcp_f32_e32 v179, v179
	v_mul_f32_e32 v108, v108, v172
	v_mul_f32_e32 v109, v109, v173
	v_mul_f32_e32 v110, v110, v174
	v_mul_f32_e32 v111, v111, v175
	v_mul_f32_e32 v100, v100, v176
	v_mul_f32_e32 v101, v101, v177
	v_mul_f32_e32 v102, v102, v178
	v_mul_f32_e32 v103, v103, v179
	v_mul_f32_e32 v108, v104, v108
	v_mul_f32_e32 v109, v105, v109
	v_mul_f32_e32 v110, v106, v110
	v_mul_f32_e32 v111, v107, v111
	v_mul_f32_e32 v100, v96, v100
	v_mul_f32_e32 v101, v97, v101
	v_mul_f32_e32 v102, v98, v102
	v_mul_f32_e32 v103, v99, v103
	v_mad_i64_i32 v[184:185], s[2:3], v182, s64, v[186:187]
; DI unsigned cvt_pk(float lo, float hi) { unsigned r; asm("v_cvt_pk_bf16_f32 %0, %1, %2" : "=v"(r) : "v"(lo), "v"(hi)); return r; }
; DI float siluf_(float x) { return x * sigmoidf_(x); }
;     __device__ __forceinline__ void operator()(const f32x4 (&acc)[2][2][4][2], const Unit& u, int wr, int wc, int fr, int fq) const {
;         const int row0 = u.pm * BM + wr * 64 + fr, col0 = u.pn * 128 + wc * 32 + 8 * fq;
; #pragma unroll
;         for (int ai = 0; ai < 2; ++ai)
; #pragma unroll
;             for (int m = 0; m < 4; ++m) {
;                 const int row = row0 + ai * HALF + m * 16;
;                 const float rs = rsqrtf(ss[row] * (1.f / DM) + EPS);
;                 float h[8];
; #pragma unroll
;                 for (int n = 0; n < 2; ++n)
; #pragma unroll
;                     for (int j = 0; j < 4; ++j) { const float gg = acc[ai][0][m][n][j] * rs, uu = acc[ai][1][m][n][j] * rs; h[4 * n + j] = siluf_(gg) * uu; }
;                 u32x4 w; w.x = cvt_pk(h[0], h[1]); w.y = cvt_pk(h[2], h[3]); w.z = cvt_pk(h[4], h[5]); w.w = cvt_pk(h[6], h[7]);
;                 *(u32x4*)(H + (size_t)row * DFF + col0) = w;
;             }
	v_cvt_pk_bf16_f32 v172, v108, v109
	v_cvt_pk_bf16_f32 v173, v110, v111
	v_cvt_pk_bf16_f32 v174, v100, v101
	v_cvt_pk_bf16_f32 v175, v102, v103
	v_lshl_add_u64 v[184:185], v[184:185], 0, v[188:189]
	global_store_dwordx4 v[184:185], v[172:175], off
	v_fmamk_f32 v180, v163, 0x3a800000, v217
	v_cmp_gt_f32_e32 vcc, s15, v180
	v_mul_f32_e32 v181, 0x4b800000, v180
	s_nop 0
	v_cndmask_b32_e32 v180, v180, v181, vcc
	v_rsq_f32_e32 v180, v180
	v_add_u32_e32 v182, 32, v138
	v_mul_f32_e32 v181, 0x45800000, v180
	v_cndmask_b32_e32 v180, v180, v181, vcc
	v_mul_f32_e32 v92, v92, v180
	v_mul_f32_e32 v88, v88, v180
	v_mul_f32_e32 v93, v93, v180
	v_mul_f32_e32 v89, v89, v180
	v_mul_f32_e32 v94, v94, v180
	v_mul_f32_e32 v90, v90, v180
	v_mul_f32_e32 v95, v95, v180
	v_mul_f32_e32 v91, v91, v180
	v_mul_f32_e32 v84, v84, v180
	v_mul_f32_e32 v80, v80, v180
	v_mul_f32_e32 v85, v85, v180
	v_mul_f32_e32 v81, v81, v180
	v_mul_f32_e32 v86, v86, v180
	v_mul_f32_e32 v82, v82, v180
	v_mul_f32_e32 v87, v87, v180
	v_mul_f32_e32 v83, v83, v180
	v_mul_f32_e32 v172, 0xbfb8aa3b, v92
	v_mul_f32_e32 v173, 0xbfb8aa3b, v93
	v_mul_f32_e32 v174, 0xbfb8aa3b, v94
	v_mul_f32_e32 v175, 0xbfb8aa3b, v95
	v_mul_f32_e32 v176, 0xbfb8aa3b, v84
	v_mul_f32_e32 v177, 0xbfb8aa3b, v85
	v_mul_f32_e32 v178, 0xbfb8aa3b, v86
	v_mul_f32_e32 v179, 0xbfb8aa3b, v87
	v_exp_f32_e32 v172, v172
	v_exp_f32_e32 v173, v173
	v_exp_f32_e32 v174, v174
	v_exp_f32_e32 v175, v175
	v_exp_f32_e32 v176, v176
	v_exp_f32_e32 v177, v177
	v_exp_f32_e32 v178, v178
	v_exp_f32_e32 v179, v179
	v_add_f32_e32 v172, 1.0, v172
	v_add_f32_e32 v173, 1.0, v173
	v_add_f32_e32 v174, 1.0, v174
	v_add_f32_e32 v175, 1.0, v175
	v_add_f32_e32 v176, 1.0, v176
	v_add_f32_e32 v177, 1.0, v177
	v_add_f32_e32 v178, 1.0, v178
	v_add_f32_e32 v179, 1.0, v179
	v_rcp_f32_e32 v172, v172
	v_rcp_f32_e32 v173, v173
	v_rcp_f32_e32 v174, v174
	v_rcp_f32_e32 v175, v175
	v_rcp_f32_e32 v176, v176
	v_rcp_f32_e32 v177, v177
	v_rcp_f32_e32 v178, v178
	v_rcp_f32_e32 v179, v179
	v_mul_f32_e32 v92, v92, v172
	v_mul_f32_e32 v93, v93, v173
	v_mul_f32_e32 v94, v94, v174
	v_mul_f32_e32 v95, v95, v175
	v_mul_f32_e32 v84, v84, v176
	v_mul_f32_e32 v85, v85, v177
	v_mul_f32_e32 v86, v86, v178
	v_mul_f32_e32 v87, v87, v179
	v_mul_f32_e32 v92, v88, v92
	v_mul_f32_e32 v93, v89, v93
	v_mul_f32_e32 v94, v90, v94
	v_mul_f32_e32 v95, v91, v95
	v_mul_f32_e32 v84, v80, v84
	v_mul_f32_e32 v85, v81, v85
	v_mul_f32_e32 v86, v82, v86
	v_mul_f32_e32 v87, v83, v87
	v_mad_i64_i32 v[184:185], s[2:3], v182, s64, v[186:187]
	v_cvt_pk_bf16_f32 v172, v92, v93
	v_cvt_pk_bf16_f32 v173, v94, v95
	v_cvt_pk_bf16_f32 v174, v84, v85
	v_cvt_pk_bf16_f32 v175, v86, v87
	v_lshl_add_u64 v[184:185], v[184:185], 0, v[188:189]
	global_store_dwordx4 v[184:185], v[172:175], off
	v_fmamk_f32 v180, v164, 0x3a800000, v217
	v_cmp_gt_f32_e32 vcc, s15, v180
	v_mul_f32_e32 v181, 0x4b800000, v180
	s_nop 0
	v_cndmask_b32_e32 v180, v180, v181, vcc
	v_rsq_f32_e32 v180, v180
	v_add_u32_e32 v182, 48, v138
	v_mul_f32_e32 v181, 0x45800000, v180
	v_cndmask_b32_e32 v180, v180, v181, vcc
	v_mul_f32_e32 v76, v76, v180
	v_mul_f32_e32 v72, v72, v180
	v_mul_f32_e32 v77, v77, v180
	v_mul_f32_e32 v73, v73, v180
	v_mul_f32_e32 v78, v78, v180
	v_mul_f32_e32 v74, v74, v180
	v_mul_f32_e32 v79, v79, v180
	v_mul_f32_e32 v75, v75, v180
	v_mul_f32_e32 v68, v68, v180
	v_mul_f32_e32 v64, v64, v180
	v_mul_f32_e32 v69, v69, v180
	v_mul_f32_e32 v65, v65, v180
	v_mul_f32_e32 v70, v70, v180
	v_mul_f32_e32 v66, v66, v180
	v_mul_f32_e32 v71, v71, v180
	v_mul_f32_e32 v67, v67, v180
	v_mul_f32_e32 v172, 0xbfb8aa3b, v76
	v_mul_f32_e32 v173, 0xbfb8aa3b, v77
	v_mul_f32_e32 v174, 0xbfb8aa3b, v78
	v_mul_f32_e32 v175, 0xbfb8aa3b, v79
	v_mul_f32_e32 v176, 0xbfb8aa3b, v68
	v_mul_f32_e32 v177, 0xbfb8aa3b, v69
	v_mul_f32_e32 v178, 0xbfb8aa3b, v70
	v_mul_f32_e32 v179, 0xbfb8aa3b, v71
	v_exp_f32_e32 v172, v172
	v_exp_f32_e32 v173, v173
	v_exp_f32_e32 v174, v174
	v_exp_f32_e32 v175, v175
	v_exp_f32_e32 v176, v176
	v_exp_f32_e32 v177, v177
	v_exp_f32_e32 v178, v178
	v_exp_f32_e32 v179, v179
	v_add_f32_e32 v172, 1.0, v172
	v_add_f32_e32 v173, 1.0, v173
	v_add_f32_e32 v174, 1.0, v174
	v_add_f32_e32 v175, 1.0, v175
	v_add_f32_e32 v176, 1.0, v176
	v_add_f32_e32 v177, 1.0, v177
	v_add_f32_e32 v178, 1.0, v178
	v_add_f32_e32 v179, 1.0, v179
	v_rcp_f32_e32 v172, v172
	v_rcp_f32_e32 v173, v173
	v_rcp_f32_e32 v174, v174
	v_rcp_f32_e32 v175, v175
	v_rcp_f32_e32 v176, v176
	v_rcp_f32_e32 v177, v177
	v_rcp_f32_e32 v178, v178
	v_rcp_f32_e32 v179, v179
	v_mul_f32_e32 v76, v76, v172
	v_mul_f32_e32 v77, v77, v173
	v_mul_f32_e32 v78, v78, v174
	v_mul_f32_e32 v79, v79, v175
	v_mul_f32_e32 v68, v68, v176
	v_mul_f32_e32 v69, v69, v177
	v_mul_f32_e32 v70, v70, v178
	v_mul_f32_e32 v71, v71, v179
	v_mul_f32_e32 v76, v72, v76
	v_mul_f32_e32 v77, v73, v77
	v_mul_f32_e32 v78, v74, v78
	v_mul_f32_e32 v79, v75, v79
	v_mul_f32_e32 v68, v64, v68
	v_mul_f32_e32 v69, v65, v69
	v_mul_f32_e32 v70, v66, v70
	v_mul_f32_e32 v71, v67, v71
	v_mad_i64_i32 v[184:185], s[2:3], v182, s64, v[186:187]
	v_cvt_pk_bf16_f32 v172, v76, v77
	v_cvt_pk_bf16_f32 v173, v78, v79
	v_cvt_pk_bf16_f32 v174, v68, v69
	v_cvt_pk_bf16_f32 v175, v70, v71
	v_lshl_add_u64 v[184:185], v[184:185], 0, v[188:189]
	global_store_dwordx4 v[184:185], v[172:175], off
	v_fmamk_f32 v180, v165, 0x3a800000, v217
	v_cmp_gt_f32_e32 vcc, s15, v180
	v_mul_f32_e32 v181, 0x4b800000, v180
	s_nop 0
	v_cndmask_b32_e32 v180, v180, v181, vcc
	v_rsq_f32_e32 v180, v180
	v_add_u32_e32 v182, 128, v138
	v_mul_f32_e32 v181, 0x45800000, v180
	v_cndmask_b32_e32 v180, v180, v181, vcc
	v_mul_f32_e32 v60, v60, v180
	v_mul_f32_e32 v56, v56, v180
	v_mul_f32_e32 v61, v61, v180
; DI unsigned cvt_pk(float lo, float hi) { unsigned r; asm("v_cvt_pk_bf16_f32 %0, %1, %2" : "=v"(r) : "v"(lo), "v"(hi)); return r; }
; DI float siluf_(float x) { return x * sigmoidf_(x); }
;     __device__ __forceinline__ void operator()(const f32x4 (&acc)[2][2][4][2], const Unit& u, int wr, int wc, int fr, int fq) const {
;         const int row0 = u.pm * BM + wr * 64 + fr, col0 = u.pn * 128 + wc * 32 + 8 * fq;
; #pragma unroll
;         for (int ai = 0; ai < 2; ++ai)
; #pragma unroll
;             for (int m = 0; m < 4; ++m) {
;                 const int row = row0 + ai * HALF + m * 16;
;                 const float rs = rsqrtf(ss[row] * (1.f / DM) + EPS);
;                 float h[8];
; #pragma unroll
;                 for (int n = 0; n < 2; ++n)
; #pragma unroll
;                     for (int j = 0; j < 4; ++j) { const float gg = acc[ai][0][m][n][j] * rs, uu = acc[ai][1][m][n][j] * rs; h[4 * n + j] = siluf_(gg) * uu; }
;                 u32x4 w; w.x = cvt_pk(h[0], h[1]); w.y = cvt_pk(h[2], h[3]); w.z = cvt_pk(h[4], h[5]); w.w = cvt_pk(h[6], h[7]);
;                 *(u32x4*)(H + (size_t)row * DFF + col0) = w;
;             }
	v_mul_f32_e32 v57, v57, v180
	v_mul_f32_e32 v62, v62, v180
	v_mul_f32_e32 v58, v58, v180
	v_mul_f32_e32 v63, v63, v180
	v_mul_f32_e32 v59, v59, v180
	v_mul_f32_e32 v52, v52, v180
	v_mul_f32_e32 v48, v48, v180
	v_mul_f32_e32 v53, v53, v180
	v_mul_f32_e32 v49, v49, v180
	v_mul_f32_e32 v54, v54, v180
	v_mul_f32_e32 v50, v50, v180
	v_mul_f32_e32 v55, v55, v180
	v_mul_f32_e32 v51, v51, v180
	v_mul_f32_e32 v172, 0xbfb8aa3b, v60
	v_mul_f32_e32 v173, 0xbfb8aa3b, v61
	v_mul_f32_e32 v174, 0xbfb8aa3b, v62
	v_mul_f32_e32 v175, 0xbfb8aa3b, v63
	v_mul_f32_e32 v176, 0xbfb8aa3b, v52
	v_mul_f32_e32 v177, 0xbfb8aa3b, v53
	v_mul_f32_e32 v178, 0xbfb8aa3b, v54
	v_mul_f32_e32 v179, 0xbfb8aa3b, v55
	v_exp_f32_e32 v172, v172
	v_exp_f32_e32 v173, v173
	v_exp_f32_e32 v174, v174
	v_exp_f32_e32 v175, v175
	v_exp_f32_e32 v176, v176
	v_exp_f32_e32 v177, v177
	v_exp_f32_e32 v178, v178
	v_exp_f32_e32 v179, v179
	v_add_f32_e32 v172, 1.0, v172
	v_add_f32_e32 v173, 1.0, v173
	v_add_f32_e32 v174, 1.0, v174
	v_add_f32_e32 v175, 1.0, v175
	v_add_f32_e32 v176, 1.0, v176
	v_add_f32_e32 v177, 1.0, v177
	v_add_f32_e32 v178, 1.0, v178
	v_add_f32_e32 v179, 1.0, v179
	v_rcp_f32_e32 v172, v172
	v_rcp_f32_e32 v173, v173
	v_rcp_f32_e32 v174, v174
	v_rcp_f32_e32 v175, v175
	v_rcp_f32_e32 v176, v176
	v_rcp_f32_e32 v177, v177
	v_rcp_f32_e32 v178, v178
	v_rcp_f32_e32 v179, v179
	v_mul_f32_e32 v60, v60, v172
	v_mul_f32_e32 v61, v61, v173
	v_mul_f32_e32 v62, v62, v174
	v_mul_f32_e32 v63, v63, v175
	v_mul_f32_e32 v52, v52, v176
	v_mul_f32_e32 v53, v53, v177
	v_mul_f32_e32 v54, v54, v178
	v_mul_f32_e32 v55, v55, v179
	v_mul_f32_e32 v60, v56, v60
	v_mul_f32_e32 v61, v57, v61
	v_mul_f32_e32 v62, v58, v62
	v_mul_f32_e32 v63, v59, v63
	v_mul_f32_e32 v52, v48, v52
	v_mul_f32_e32 v53, v49, v53
	v_mul_f32_e32 v54, v50, v54
	v_mul_f32_e32 v55, v51, v55
	v_mad_i64_i32 v[184:185], s[2:3], v182, s64, v[186:187]
	v_cvt_pk_bf16_f32 v172, v60, v61
	v_cvt_pk_bf16_f32 v173, v62, v63
	v_cvt_pk_bf16_f32 v174, v52, v53
	v_cvt_pk_bf16_f32 v175, v54, v55
	v_lshl_add_u64 v[184:185], v[184:185], 0, v[188:189]
	global_store_dwordx4 v[184:185], v[172:175], off
	v_fmamk_f32 v180, v166, 0x3a800000, v217
	v_cmp_gt_f32_e32 vcc, s15, v180
	v_mul_f32_e32 v181, 0x4b800000, v180
	s_nop 0
	v_cndmask_b32_e32 v180, v180, v181, vcc
	v_rsq_f32_e32 v180, v180
	v_add_u32_e32 v182, 144, v138
	v_mul_f32_e32 v181, 0x45800000, v180
	v_cndmask_b32_e32 v180, v180, v181, vcc
	v_mul_f32_e32 v44, v44, v180
	v_mul_f32_e32 v40, v40, v180
	v_mul_f32_e32 v45, v45, v180
	v_mul_f32_e32 v41, v41, v180
	v_mul_f32_e32 v46, v46, v180
	v_mul_f32_e32 v42, v42, v180
	v_mul_f32_e32 v47, v47, v180
	v_mul_f32_e32 v43, v43, v180
	v_mul_f32_e32 v36, v36, v180
	v_mul_f32_e32 v32, v32, v180
	v_mul_f32_e32 v37, v37, v180
	v_mul_f32_e32 v33, v33, v180
	v_mul_f32_e32 v38, v38, v180
	v_mul_f32_e32 v34, v34, v180
	v_mul_f32_e32 v39, v39, v180
	v_mul_f32_e32 v35, v35, v180
	v_mul_f32_e32 v172, 0xbfb8aa3b, v44
	v_mul_f32_e32 v173, 0xbfb8aa3b, v45
	v_mul_f32_e32 v174, 0xbfb8aa3b, v46
	v_mul_f32_e32 v175, 0xbfb8aa3b, v47
	v_mul_f32_e32 v176, 0xbfb8aa3b, v36
	v_mul_f32_e32 v177, 0xbfb8aa3b, v37
	v_mul_f32_e32 v178, 0xbfb8aa3b, v38
	v_mul_f32_e32 v179, 0xbfb8aa3b, v39
	v_exp_f32_e32 v172, v172
	v_exp_f32_e32 v173, v173
	v_exp_f32_e32 v174, v174
	v_exp_f32_e32 v175, v175
	v_exp_f32_e32 v176, v176
	v_exp_f32_e32 v177, v177
	v_exp_f32_e32 v178, v178
	v_exp_f32_e32 v179, v179
	v_add_f32_e32 v172, 1.0, v172
	v_add_f32_e32 v173, 1.0, v173
	v_add_f32_e32 v174, 1.0, v174
	v_add_f32_e32 v175, 1.0, v175
	v_add_f32_e32 v176, 1.0, v176
	v_add_f32_e32 v177, 1.0, v177
	v_add_f32_e32 v178, 1.0, v178
	v_add_f32_e32 v179, 1.0, v179
	v_rcp_f32_e32 v172, v172
	v_rcp_f32_e32 v173, v173
	v_rcp_f32_e32 v174, v174
	v_rcp_f32_e32 v175, v175
	v_rcp_f32_e32 v176, v176
	v_rcp_f32_e32 v177, v177
	v_rcp_f32_e32 v178, v178
	v_rcp_f32_e32 v179, v179
	v_mul_f32_e32 v44, v44, v172
	v_mul_f32_e32 v45, v45, v173
	v_mul_f32_e32 v46, v46, v174
	v_mul_f32_e32 v47, v47, v175
	v_mul_f32_e32 v36, v36, v176
	v_mul_f32_e32 v37, v37, v177
	v_mul_f32_e32 v38, v38, v178
	v_mul_f32_e32 v39, v39, v179
	v_mul_f32_e32 v44, v40, v44
	v_mul_f32_e32 v45, v41, v45
	v_mul_f32_e32 v46, v42, v46
	v_mul_f32_e32 v47, v43, v47
	v_mul_f32_e32 v36, v32, v36
	v_mul_f32_e32 v37, v33, v37
	v_mul_f32_e32 v38, v34, v38
	v_mul_f32_e32 v39, v35, v39
	v_mad_i64_i32 v[184:185], s[2:3], v182, s64, v[186:187]
	v_cvt_pk_bf16_f32 v172, v44, v45
	v_cvt_pk_bf16_f32 v173, v46, v47
	v_cvt_pk_bf16_f32 v174, v36, v37
	v_cvt_pk_bf16_f32 v175, v38, v39
	v_lshl_add_u64 v[184:185], v[184:185], 0, v[188:189]
	global_store_dwordx4 v[184:185], v[172:175], off
	v_fmamk_f32 v180, v167, 0x3a800000, v217
	v_cmp_gt_f32_e32 vcc, s15, v180
	v_mul_f32_e32 v181, 0x4b800000, v180
	s_nop 0
	v_cndmask_b32_e32 v180, v180, v181, vcc
	v_rsq_f32_e32 v180, v180
	v_add_u32_e32 v182, 160, v138
	v_mul_f32_e32 v181, 0x45800000, v180
; DI unsigned cvt_pk(float lo, float hi) { unsigned r; asm("v_cvt_pk_bf16_f32 %0, %1, %2" : "=v"(r) : "v"(lo), "v"(hi)); return r; }
; DI float siluf_(float x) { return x * sigmoidf_(x); }
;     __device__ __forceinline__ void operator()(const f32x4 (&acc)[2][2][4][2], const Unit& u, int wr, int wc, int fr, int fq) const {
;         const int row0 = u.pm * BM + wr * 64 + fr, col0 = u.pn * 128 + wc * 32 + 8 * fq;
; #pragma unroll
;         for (int ai = 0; ai < 2; ++ai)
; #pragma unroll
;             for (int m = 0; m < 4; ++m) {
;                 const int row = row0 + ai * HALF + m * 16;
;                 const float rs = rsqrtf(ss[row] * (1.f / DM) + EPS);
;                 float h[8];
; #pragma unroll
;                 for (int n = 0; n < 2; ++n)
; #pragma unroll
;                     for (int j = 0; j < 4; ++j) { const float gg = acc[ai][0][m][n][j] * rs, uu = acc[ai][1][m][n][j] * rs; h[4 * n + j] = siluf_(gg) * uu; }
;                 u32x4 w; w.x = cvt_pk(h[0], h[1]); w.y = cvt_pk(h[2], h[3]); w.z = cvt_pk(h[4], h[5]); w.w = cvt_pk(h[6], h[7]);
;                 *(u32x4*)(H + (size_t)row * DFF + col0) = w;
;             }
	v_cndmask_b32_e32 v180, v180, v181, vcc
	v_mul_f32_e32 v28, v28, v180
	v_mul_f32_e32 v24, v24, v180
	v_mul_f32_e32 v29, v29, v180
	v_mul_f32_e32 v25, v25, v180
	v_mul_f32_e32 v30, v30, v180
	v_mul_f32_e32 v26, v26, v180
	v_mul_f32_e32 v31, v31, v180
	v_mul_f32_e32 v27, v27, v180
	v_mul_f32_e32 v20, v20, v180
	v_mul_f32_e32 v16, v16, v180
	v_mul_f32_e32 v21, v21, v180
	v_mul_f32_e32 v17, v17, v180
	v_mul_f32_e32 v22, v22, v180
	v_mul_f32_e32 v18, v18, v180
	v_mul_f32_e32 v23, v23, v180
	v_mul_f32_e32 v19, v19, v180
	v_mul_f32_e32 v172, 0xbfb8aa3b, v28
	v_mul_f32_e32 v173, 0xbfb8aa3b, v29
	v_mul_f32_e32 v174, 0xbfb8aa3b, v30
	v_mul_f32_e32 v175, 0xbfb8aa3b, v31
	v_mul_f32_e32 v176, 0xbfb8aa3b, v20
	v_mul_f32_e32 v177, 0xbfb8aa3b, v21
	v_mul_f32_e32 v178, 0xbfb8aa3b, v22
	v_mul_f32_e32 v179, 0xbfb8aa3b, v23
	v_exp_f32_e32 v172, v172
	v_exp_f32_e32 v173, v173
	v_exp_f32_e32 v174, v174
	v_exp_f32_e32 v175, v175
	v_exp_f32_e32 v176, v176
	v_exp_f32_e32 v177, v177
	v_exp_f32_e32 v178, v178
	v_exp_f32_e32 v179, v179
	v_add_f32_e32 v172, 1.0, v172
	v_add_f32_e32 v173, 1.0, v173
	v_add_f32_e32 v174, 1.0, v174
	v_add_f32_e32 v175, 1.0, v175
	v_add_f32_e32 v176, 1.0, v176
	v_add_f32_e32 v177, 1.0, v177
	v_add_f32_e32 v178, 1.0, v178
	v_add_f32_e32 v179, 1.0, v179
	v_rcp_f32_e32 v172, v172
	v_rcp_f32_e32 v173, v173
	v_rcp_f32_e32 v174, v174
	v_rcp_f32_e32 v175, v175
	v_rcp_f32_e32 v176, v176
	v_rcp_f32_e32 v177, v177
	v_rcp_f32_e32 v178, v178
	v_rcp_f32_e32 v179, v179
	v_mul_f32_e32 v28, v28, v172
	v_mul_f32_e32 v29, v29, v173
	v_mul_f32_e32 v30, v30, v174
	v_mul_f32_e32 v31, v31, v175
	v_mul_f32_e32 v20, v20, v176
	v_mul_f32_e32 v21, v21, v177
	v_mul_f32_e32 v22, v22, v178
	v_mul_f32_e32 v23, v23, v179
	v_mul_f32_e32 v28, v24, v28
	v_mul_f32_e32 v29, v25, v29
	v_mul_f32_e32 v30, v26, v30
	v_mul_f32_e32 v31, v27, v31
	v_mul_f32_e32 v20, v16, v20
	v_mul_f32_e32 v21, v17, v21
	v_mul_f32_e32 v22, v18, v22
	v_mul_f32_e32 v23, v19, v23
	v_mad_i64_i32 v[184:185], s[2:3], v182, s64, v[186:187]
	v_cvt_pk_bf16_f32 v172, v28, v29
	v_cvt_pk_bf16_f32 v173, v30, v31
	v_cvt_pk_bf16_f32 v174, v20, v21
	v_cvt_pk_bf16_f32 v175, v22, v23
	v_lshl_add_u64 v[184:185], v[184:185], 0, v[188:189]
	global_store_dwordx4 v[184:185], v[172:175], off
	v_fmamk_f32 v180, v168, 0x3a800000, v217
	v_cmp_gt_f32_e32 vcc, s15, v180
	v_mul_f32_e32 v181, 0x4b800000, v180
	s_nop 0
	v_cndmask_b32_e32 v180, v180, v181, vcc
	v_rsq_f32_e32 v180, v180
	v_add_u32_e32 v182, 176, v138
	v_mul_f32_e32 v181, 0x45800000, v180
	v_cndmask_b32_e32 v180, v180, v181, vcc
	v_mul_f32_e32 v12, v12, v180
	v_mul_f32_e32 v8, v8, v180
	v_mul_f32_e32 v13, v13, v180
	v_mul_f32_e32 v9, v9, v180
	v_mul_f32_e32 v14, v14, v180
	v_mul_f32_e32 v10, v10, v180
	v_mul_f32_e32 v15, v15, v180
	v_mul_f32_e32 v11, v11, v180
	v_mul_f32_e32 v4, v4, v180
	v_mul_f32_e32 v0, v0, v180
	v_mul_f32_e32 v5, v5, v180
	v_mul_f32_e32 v1, v1, v180
	v_mul_f32_e32 v6, v6, v180
	v_mul_f32_e32 v2, v2, v180
	v_mul_f32_e32 v7, v7, v180
	v_mul_f32_e32 v3, v3, v180
	v_mul_f32_e32 v172, 0xbfb8aa3b, v12
	v_mul_f32_e32 v173, 0xbfb8aa3b, v13
	v_mul_f32_e32 v174, 0xbfb8aa3b, v14
	v_mul_f32_e32 v175, 0xbfb8aa3b, v15
	v_mul_f32_e32 v176, 0xbfb8aa3b, v4
	v_mul_f32_e32 v177, 0xbfb8aa3b, v5
	v_mul_f32_e32 v178, 0xbfb8aa3b, v6
	v_mul_f32_e32 v179, 0xbfb8aa3b, v7
	v_exp_f32_e32 v172, v172
	v_exp_f32_e32 v173, v173
	v_exp_f32_e32 v174, v174
	v_exp_f32_e32 v175, v175
	v_exp_f32_e32 v176, v176
	v_exp_f32_e32 v177, v177
	v_exp_f32_e32 v178, v178
	v_exp_f32_e32 v179, v179
	v_add_f32_e32 v172, 1.0, v172
	v_add_f32_e32 v173, 1.0, v173
	v_add_f32_e32 v174, 1.0, v174
	v_add_f32_e32 v175, 1.0, v175
	v_add_f32_e32 v176, 1.0, v176
	v_add_f32_e32 v177, 1.0, v177
	v_add_f32_e32 v178, 1.0, v178
	v_add_f32_e32 v179, 1.0, v179
	v_rcp_f32_e32 v172, v172
	v_rcp_f32_e32 v173, v173
	v_rcp_f32_e32 v174, v174
	v_rcp_f32_e32 v175, v175
	v_rcp_f32_e32 v176, v176
	v_rcp_f32_e32 v177, v177
	v_rcp_f32_e32 v178, v178
	v_rcp_f32_e32 v179, v179
	v_mul_f32_e32 v12, v12, v172
	v_mul_f32_e32 v13, v13, v173
	v_mul_f32_e32 v14, v14, v174
	v_mul_f32_e32 v15, v15, v175
	v_mul_f32_e32 v4, v4, v176
	v_mul_f32_e32 v5, v5, v177
	v_mul_f32_e32 v6, v6, v178
	v_mul_f32_e32 v7, v7, v179
	v_mul_f32_e32 v12, v8, v12
	v_mul_f32_e32 v13, v9, v13
	v_mul_f32_e32 v14, v10, v14
	v_mul_f32_e32 v15, v11, v15
	v_mul_f32_e32 v4, v0, v4
	v_mul_f32_e32 v5, v1, v5
	v_mul_f32_e32 v6, v2, v6
	v_mul_f32_e32 v7, v3, v7
	v_mad_i64_i32 v[184:185], s[2:3], v182, s64, v[186:187]
	v_cvt_pk_bf16_f32 v172, v12, v13
	v_cvt_pk_bf16_f32 v173, v14, v15
	v_cvt_pk_bf16_f32 v174, v4, v5
	v_cvt_pk_bf16_f32 v175, v6, v7
	v_lshl_add_u64 v[184:185], v[184:185], 0, v[188:189]
	global_store_dwordx4 v[184:185], v[172:175], off
	s_mov_b64 s[2:3], -1
	s_andn2_b64 vcc, exec, s[4:5]
	s_cbranch_vccnz .LBB0_286
	s_andn2_b64 vcc, exec, s[6:7]
	s_cbranch_vccnz .LBB0_285
	s_barrier
	s_branch .LBB0_285

; DI unsigned cvt_pk(float lo, float hi) { unsigned r; asm("v_cvt_pk_bf16_f32 %0, %1, %2" : "=v"(r) : "v"(lo), "v"(hi)); return r; }
; DI float siluf_(float x) { return x * sigmoidf_(x); }
;     __device__ __forceinline__ void operator()(const f32x4 (&acc)[2][2][4][2], const Unit& u, int wr, int wc, int fr, int fq) const {
;         const int row0 = u.pm * BM + wr * 64 + fr, col0 = u.pn * 128 + wc * 32 + 8 * fq;
; #pragma unroll
;         for (int ai = 0; ai < 2; ++ai)
; #pragma unroll
;             for (int m = 0; m < 4; ++m) {
;                 const int row = row0 + ai * HALF + m * 16;
;                 const float rs = rsqrtf(ss[row] * (1.f / DM) + EPS);
;                 float h[8];
; #pragma unroll
;                 for (int n = 0; n < 2; ++n)
; #pragma unroll
;                     for (int j = 0; j < 4; ++j) { const float gg = acc[ai][0][m][n][j] * rs, uu = acc[ai][1][m][n][j] * rs; h[4 * n + j] = siluf_(gg) * uu; }
;                 u32x4 w; w.x = cvt_pk(h[0], h[1]); w.y = cvt_pk(h[2], h[3]); w.z = cvt_pk(h[4], h[5]); w.w = cvt_pk(h[6], h[7]);
;                 *(u32x4*)(H + (size_t)row * DFF + col0) = w;
;             }
.LBB0_1298:
	v_lshl_add_u32 v138, s41, 8, v155
	v_ashrrev_i32_e32 v139, 31, v138
	v_lshl_add_u64 v[140:141], v[138:139], 2, s[10:11]
	global_load_dword v139, v[140:141], off
	global_load_dword v162, v[140:141], off offset:64
	global_load_dword v163, v[140:141], off offset:128
	global_load_dword v164, v[140:141], off offset:192
	global_load_dword v165, v[140:141], off offset:512
	global_load_dword v166, v[140:141], off offset:576
	global_load_dword v167, v[140:141], off offset:640
	global_load_dword v168, v[140:141], off offset:704
	s_mov_b32 s15, 0x800000
	v_lshl_or_b32 v142, s40, 7, v157
	v_ashrrev_i32_e32 v143, 31, v142
	v_mov_b64_e32 v[186:187], s[4:5]
	v_lshlrev_b64 v[188:189], 1, v[142:143]
	s_waitcnt vmcnt(0)
	v_fmamk_f32 v180, v139, 0x3a800000, v217
	v_cmp_gt_f32_e32 vcc, s15, v180
	v_mul_f32_e32 v181, 0x4b800000, v180
	s_nop 0
	v_cndmask_b32_e32 v180, v180, v181, vcc
	v_rsq_f32_e32 v180, v180
	v_add_u32_e32 v182, 0, v138
	v_mul_f32_e32 v181, 0x45800000, v180
	v_cndmask_b32_e32 v180, v180, v181, vcc
	v_mul_f32_e32 v124, v124, v180
	v_mul_f32_e32 v120, v120, v180
	v_mul_f32_e32 v125, v125, v180
	v_mul_f32_e32 v121, v121, v180
	v_mul_f32_e32 v126, v126, v180
	v_mul_f32_e32 v122, v122, v180
	v_mul_f32_e32 v127, v127, v180
	v_mul_f32_e32 v123, v123, v180
	v_mul_f32_e32 v116, v116, v180
	v_mul_f32_e32 v112, v112, v180
	v_mul_f32_e32 v117, v117, v180
	v_mul_f32_e32 v113, v113, v180
	v_mul_f32_e32 v118, v118, v180
	v_mul_f32_e32 v114, v114, v180
	v_mul_f32_e32 v119, v119, v180
	v_mul_f32_e32 v115, v115, v180
	v_mul_f32_e32 v172, 0xbfb8aa3b, v124
	v_mul_f32_e32 v173, 0xbfb8aa3b, v125
	v_mul_f32_e32 v174, 0xbfb8aa3b, v126
	v_mul_f32_e32 v175, 0xbfb8aa3b, v127
	v_mul_f32_e32 v176, 0xbfb8aa3b, v116
	v_mul_f32_e32 v177, 0xbfb8aa3b, v117
	v_mul_f32_e32 v178, 0xbfb8aa3b, v118
	v_mul_f32_e32 v179, 0xbfb8aa3b, v119
	v_exp_f32_e32 v172, v172
	v_exp_f32_e32 v173, v173
	v_exp_f32_e32 v174, v174
	v_exp_f32_e32 v175, v175
	v_exp_f32_e32 v176, v176
	v_exp_f32_e32 v177, v177
	v_exp_f32_e32 v178, v178
	v_exp_f32_e32 v179, v179
	v_add_f32_e32 v172, 1.0, v172
	v_add_f32_e32 v173, 1.0, v173
	v_add_f32_e32 v174, 1.0, v174
	v_add_f32_e32 v175, 1.0, v175
	v_add_f32_e32 v176, 1.0, v176
	v_add_f32_e32 v177, 1.0, v177
	v_add_f32_e32 v178, 1.0, v178
	v_add_f32_e32 v179, 1.0, v179
	v_rcp_f32_e32 v172, v172
	v_rcp_f32_e32 v173, v173
	v_rcp_f32_e32 v174, v174
	v_rcp_f32_e32 v175, v175
	v_rcp_f32_e32 v176, v176
	v_rcp_f32_e32 v177, v177
	v_rcp_f32_e32 v178, v178
	v_rcp_f32_e32 v179, v179
	v_mul_f32_e32 v124, v124, v172
	v_mul_f32_e32 v125, v125, v173
	v_mul_f32_e32 v126, v126, v174
	v_mul_f32_e32 v127, v127, v175
	v_mul_f32_e32 v116, v116, v176
	v_mul_f32_e32 v117, v117, v177
	v_mul_f32_e32 v118, v118, v178
	v_mul_f32_e32 v119, v119, v179
	v_mul_f32_e32 v124, v120, v124
	v_mul_f32_e32 v125, v121, v125
	v_mul_f32_e32 v126, v122, v126
	v_mul_f32_e32 v127, v123, v127
	v_mul_f32_e32 v116, v112, v116
	v_mul_f32_e32 v117, v113, v117
	v_mul_f32_e32 v118, v114, v118
	v_mul_f32_e32 v119, v115, v119
	v_mad_i64_i32 v[184:185], s[22:23], v182, s64, v[186:187]
	v_cvt_pk_bf16_f32 v172, v124, v125
	v_cvt_pk_bf16_f32 v173, v126, v127
	v_cvt_pk_bf16_f32 v174, v116, v117
	v_cvt_pk_bf16_f32 v175, v118, v119
	v_lshl_add_u64 v[184:185], v[184:185], 0, v[188:189]
	global_store_dwordx4 v[184:185], v[172:175], off
	v_fmamk_f32 v180, v162, 0x3a800000, v217
	v_cmp_gt_f32_e32 vcc, s15, v180
	v_mul_f32_e32 v181, 0x4b800000, v180
	s_nop 0
	v_cndmask_b32_e32 v180, v180, v181, vcc
	v_rsq_f32_e32 v180, v180
	v_add_u32_e32 v182, 16, v138
	v_mul_f32_e32 v181, 0x45800000, v180
	v_cndmask_b32_e32 v180, v180, v181, vcc
	v_mul_f32_e32 v108, v108, v180
	v_mul_f32_e32 v104, v104, v180
	v_mul_f32_e32 v109, v109, v180
	v_mul_f32_e32 v105, v105, v180
	v_mul_f32_e32 v110, v110, v180
	v_mul_f32_e32 v106, v106, v180
	v_mul_f32_e32 v111, v111, v180
	v_mul_f32_e32 v107, v107, v180
	v_mul_f32_e32 v100, v100, v180
	v_mul_f32_e32 v96, v96, v180
	v_mul_f32_e32 v101, v101, v180
	v_mul_f32_e32 v97, v97, v180
	v_mul_f32_e32 v102, v102, v180
	v_mul_f32_e32 v98, v98, v180
	v_mul_f32_e32 v103, v103, v180
	v_mul_f32_e32 v99, v99, v180
	v_mul_f32_e32 v172, 0xbfb8aa3b, v108
	v_mul_f32_e32 v173, 0xbfb8aa3b, v109
	v_mul_f32_e32 v174, 0xbfb8aa3b, v110
	v_mul_f32_e32 v175, 0xbfb8aa3b, v111
	v_mul_f32_e32 v176, 0xbfb8aa3b, v100
	v_mul_f32_e32 v177, 0xbfb8aa3b, v101
	v_mul_f32_e32 v178, 0xbfb8aa3b, v102
	v_mul_f32_e32 v179, 0xbfb8aa3b, v103
	v_exp_f32_e32 v172, v172
	v_exp_f32_e32 v173, v173
	v_exp_f32_e32 v174, v174
	v_exp_f32_e32 v175, v175
	v_exp_f32_e32 v176, v176
	v_exp_f32_e32 v177, v177
	v_exp_f32_e32 v178, v178
	v_exp_f32_e32 v179, v179
	v_add_f32_e32 v172, 1.0, v172
	v_add_f32_e32 v173, 1.0, v173
	v_add_f32_e32 v174, 1.0, v174
	v_add_f32_e32 v175, 1.0, v175
	v_add_f32_e32 v176, 1.0, v176
	v_add_f32_e32 v177, 1.0, v177
	v_add_f32_e32 v178, 1.0, v178
	v_add_f32_e32 v179, 1.0, v179
	v_rcp_f32_e32 v172, v172
	v_rcp_f32_e32 v173, v173
	v_rcp_f32_e32 v174, v174
	v_rcp_f32_e32 v175, v175
	v_rcp_f32_e32 v176, v176
	v_rcp_f32_e32 v177, v177
	v_rcp_f32_e32 v178, v178
	v_rcp_f32_e32 v179, v179
	v_mul_f32_e32 v108, v108, v172
	v_mul_f32_e32 v109, v109, v173
	v_mul_f32_e32 v110, v110, v174
	v_mul_f32_e32 v111, v111, v175
	v_mul_f32_e32 v100, v100, v176
	v_mul_f32_e32 v101, v101, v177
	v_mul_f32_e32 v102, v102, v178
	v_mul_f32_e32 v103, v103, v179
	v_mul_f32_e32 v108, v104, v108
	v_mul_f32_e32 v109, v105, v109
	v_mul_f32_e32 v110, v106, v110
	v_mul_f32_e32 v111, v107, v111
	v_mul_f32_e32 v100, v96, v100
	v_mul_f32_e32 v101, v97, v101
	v_mul_f32_e32 v102, v98, v102
	v_mul_f32_e32 v103, v99, v103
	v_mad_i64_i32 v[184:185], s[22:23], v182, s64, v[186:187]
; DI unsigned cvt_pk(float lo, float hi) { unsigned r; asm("v_cvt_pk_bf16_f32 %0, %1, %2" : "=v"(r) : "v"(lo), "v"(hi)); return r; }
; DI float siluf_(float x) { return x * sigmoidf_(x); }
;     __device__ __forceinline__ void operator()(const f32x4 (&acc)[2][2][4][2], const Unit& u, int wr, int wc, int fr, int fq) const {
;         const int row0 = u.pm * BM + wr * 64 + fr, col0 = u.pn * 128 + wc * 32 + 8 * fq;
; #pragma unroll
;         for (int ai = 0; ai < 2; ++ai)
; #pragma unroll
;             for (int m = 0; m < 4; ++m) {
;                 const int row = row0 + ai * HALF + m * 16;
;                 const float rs = rsqrtf(ss[row] * (1.f / DM) + EPS);
;                 float h[8];
; #pragma unroll
;                 for (int n = 0; n < 2; ++n)
; #pragma unroll
;                     for (int j = 0; j < 4; ++j) { const float gg = acc[ai][0][m][n][j] * rs, uu = acc[ai][1][m][n][j] * rs; h[4 * n + j] = siluf_(gg) * uu; }
;                 u32x4 w; w.x = cvt_pk(h[0], h[1]); w.y = cvt_pk(h[2], h[3]); w.z = cvt_pk(h[4], h[5]); w.w = cvt_pk(h[6], h[7]);
;                 *(u32x4*)(H + (size_t)row * DFF + col0) = w;
;             }
	v_cvt_pk_bf16_f32 v172, v108, v109
	v_cvt_pk_bf16_f32 v173, v110, v111
	v_cvt_pk_bf16_f32 v174, v100, v101
	v_cvt_pk_bf16_f32 v175, v102, v103
	v_lshl_add_u64 v[184:185], v[184:185], 0, v[188:189]
	global_store_dwordx4 v[184:185], v[172:175], off
	v_fmamk_f32 v180, v163, 0x3a800000, v217
	v_cmp_gt_f32_e32 vcc, s15, v180
	v_mul_f32_e32 v181, 0x4b800000, v180
	s_nop 0
	v_cndmask_b32_e32 v180, v180, v181, vcc
	v_rsq_f32_e32 v180, v180
	v_add_u32_e32 v182, 32, v138
	v_mul_f32_e32 v181, 0x45800000, v180
	v_cndmask_b32_e32 v180, v180, v181, vcc
	v_mul_f32_e32 v92, v92, v180
	v_mul_f32_e32 v88, v88, v180
	v_mul_f32_e32 v93, v93, v180
	v_mul_f32_e32 v89, v89, v180
	v_mul_f32_e32 v94, v94, v180
	v_mul_f32_e32 v90, v90, v180
	v_mul_f32_e32 v95, v95, v180
	v_mul_f32_e32 v91, v91, v180
	v_mul_f32_e32 v84, v84, v180
	v_mul_f32_e32 v80, v80, v180
	v_mul_f32_e32 v85, v85, v180
	v_mul_f32_e32 v81, v81, v180
	v_mul_f32_e32 v86, v86, v180
	v_mul_f32_e32 v82, v82, v180
	v_mul_f32_e32 v87, v87, v180
	v_mul_f32_e32 v83, v83, v180
	v_mul_f32_e32 v172, 0xbfb8aa3b, v92
	v_mul_f32_e32 v173, 0xbfb8aa3b, v93
	v_mul_f32_e32 v174, 0xbfb8aa3b, v94
	v_mul_f32_e32 v175, 0xbfb8aa3b, v95
	v_mul_f32_e32 v176, 0xbfb8aa3b, v84
	v_mul_f32_e32 v177, 0xbfb8aa3b, v85
	v_mul_f32_e32 v178, 0xbfb8aa3b, v86
	v_mul_f32_e32 v179, 0xbfb8aa3b, v87
	v_exp_f32_e32 v172, v172
	v_exp_f32_e32 v173, v173
	v_exp_f32_e32 v174, v174
	v_exp_f32_e32 v175, v175
	v_exp_f32_e32 v176, v176
	v_exp_f32_e32 v177, v177
	v_exp_f32_e32 v178, v178
	v_exp_f32_e32 v179, v179
	v_add_f32_e32 v172, 1.0, v172
	v_add_f32_e32 v173, 1.0, v173
	v_add_f32_e32 v174, 1.0, v174
	v_add_f32_e32 v175, 1.0, v175
	v_add_f32_e32 v176, 1.0, v176
	v_add_f32_e32 v177, 1.0, v177
	v_add_f32_e32 v178, 1.0, v178
	v_add_f32_e32 v179, 1.0, v179
	v_rcp_f32_e32 v172, v172
	v_rcp_f32_e32 v173, v173
	v_rcp_f32_e32 v174, v174
	v_rcp_f32_e32 v175, v175
	v_rcp_f32_e32 v176, v176
	v_rcp_f32_e32 v177, v177
	v_rcp_f32_e32 v178, v178
	v_rcp_f32_e32 v179, v179
	v_mul_f32_e32 v92, v92, v172
	v_mul_f32_e32 v93, v93, v173
	v_mul_f32_e32 v94, v94, v174
	v_mul_f32_e32 v95, v95, v175
	v_mul_f32_e32 v84, v84, v176
	v_mul_f32_e32 v85, v85, v177
	v_mul_f32_e32 v86, v86, v178
	v_mul_f32_e32 v87, v87, v179
	v_mul_f32_e32 v92, v88, v92
	v_mul_f32_e32 v93, v89, v93
	v_mul_f32_e32 v94, v90, v94
	v_mul_f32_e32 v95, v91, v95
	v_mul_f32_e32 v84, v80, v84
	v_mul_f32_e32 v85, v81, v85
	v_mul_f32_e32 v86, v82, v86
	v_mul_f32_e32 v87, v83, v87
	v_mad_i64_i32 v[184:185], s[22:23], v182, s64, v[186:187]
	v_cvt_pk_bf16_f32 v172, v92, v93
	v_cvt_pk_bf16_f32 v173, v94, v95
	v_cvt_pk_bf16_f32 v174, v84, v85
	v_cvt_pk_bf16_f32 v175, v86, v87
	v_lshl_add_u64 v[184:185], v[184:185], 0, v[188:189]
	global_store_dwordx4 v[184:185], v[172:175], off
	v_fmamk_f32 v180, v164, 0x3a800000, v217
	v_cmp_gt_f32_e32 vcc, s15, v180
	v_mul_f32_e32 v181, 0x4b800000, v180
	s_nop 0
	v_cndmask_b32_e32 v180, v180, v181, vcc
	v_rsq_f32_e32 v180, v180
	v_add_u32_e32 v182, 48, v138
	v_mul_f32_e32 v181, 0x45800000, v180
	v_cndmask_b32_e32 v180, v180, v181, vcc
	v_mul_f32_e32 v76, v76, v180
	v_mul_f32_e32 v72, v72, v180
	v_mul_f32_e32 v77, v77, v180
	v_mul_f32_e32 v73, v73, v180
	v_mul_f32_e32 v78, v78, v180
	v_mul_f32_e32 v74, v74, v180
	v_mul_f32_e32 v79, v79, v180
	v_mul_f32_e32 v75, v75, v180
	v_mul_f32_e32 v68, v68, v180
	v_mul_f32_e32 v64, v64, v180
	v_mul_f32_e32 v69, v69, v180
	v_mul_f32_e32 v65, v65, v180
	v_mul_f32_e32 v70, v70, v180
	v_mul_f32_e32 v66, v66, v180
	v_mul_f32_e32 v71, v71, v180
	v_mul_f32_e32 v67, v67, v180
	v_mul_f32_e32 v172, 0xbfb8aa3b, v76
	v_mul_f32_e32 v173, 0xbfb8aa3b, v77
	v_mul_f32_e32 v174, 0xbfb8aa3b, v78
	v_mul_f32_e32 v175, 0xbfb8aa3b, v79
	v_mul_f32_e32 v176, 0xbfb8aa3b, v68
	v_mul_f32_e32 v177, 0xbfb8aa3b, v69
	v_mul_f32_e32 v178, 0xbfb8aa3b, v70
	v_mul_f32_e32 v179, 0xbfb8aa3b, v71
	v_exp_f32_e32 v172, v172
	v_exp_f32_e32 v173, v173
	v_exp_f32_e32 v174, v174
	v_exp_f32_e32 v175, v175
	v_exp_f32_e32 v176, v176
	v_exp_f32_e32 v177, v177
	v_exp_f32_e32 v178, v178
	v_exp_f32_e32 v179, v179
	v_add_f32_e32 v172, 1.0, v172
	v_add_f32_e32 v173, 1.0, v173
	v_add_f32_e32 v174, 1.0, v174
	v_add_f32_e32 v175, 1.0, v175
	v_add_f32_e32 v176, 1.0, v176
	v_add_f32_e32 v177, 1.0, v177
	v_add_f32_e32 v178, 1.0, v178
	v_add_f32_e32 v179, 1.0, v179
	v_rcp_f32_e32 v172, v172
	v_rcp_f32_e32 v173, v173
	v_rcp_f32_e32 v174, v174
	v_rcp_f32_e32 v175, v175
	v_rcp_f32_e32 v176, v176
	v_rcp_f32_e32 v177, v177
	v_rcp_f32_e32 v178, v178
	v_rcp_f32_e32 v179, v179
	v_mul_f32_e32 v76, v76, v172
	v_mul_f32_e32 v77, v77, v173
	v_mul_f32_e32 v78, v78, v174
	v_mul_f32_e32 v79, v79, v175
	v_mul_f32_e32 v68, v68, v176
	v_mul_f32_e32 v69, v69, v177
	v_mul_f32_e32 v70, v70, v178
	v_mul_f32_e32 v71, v71, v179
	v_mul_f32_e32 v76, v72, v76
	v_mul_f32_e32 v77, v73, v77
	v_mul_f32_e32 v78, v74, v78
	v_mul_f32_e32 v79, v75, v79
	v_mul_f32_e32 v68, v64, v68
	v_mul_f32_e32 v69, v65, v69
	v_mul_f32_e32 v70, v66, v70
	v_mul_f32_e32 v71, v67, v71
	v_mad_i64_i32 v[184:185], s[22:23], v182, s64, v[186:187]
	v_cvt_pk_bf16_f32 v172, v76, v77
	v_cvt_pk_bf16_f32 v173, v78, v79
	v_cvt_pk_bf16_f32 v174, v68, v69
	v_cvt_pk_bf16_f32 v175, v70, v71
	v_lshl_add_u64 v[184:185], v[184:185], 0, v[188:189]
	global_store_dwordx4 v[184:185], v[172:175], off
	v_fmamk_f32 v180, v165, 0x3a800000, v217
	v_cmp_gt_f32_e32 vcc, s15, v180
	v_mul_f32_e32 v181, 0x4b800000, v180
	s_nop 0
	v_cndmask_b32_e32 v180, v180, v181, vcc
	v_rsq_f32_e32 v180, v180
	v_add_u32_e32 v182, 128, v138
	v_mul_f32_e32 v181, 0x45800000, v180
	v_cndmask_b32_e32 v180, v180, v181, vcc
	v_mul_f32_e32 v60, v60, v180
	v_mul_f32_e32 v56, v56, v180
; DI unsigned cvt_pk(float lo, float hi) { unsigned r; asm("v_cvt_pk_bf16_f32 %0, %1, %2" : "=v"(r) : "v"(lo), "v"(hi)); return r; }
; DI float siluf_(float x) { return x * sigmoidf_(x); }
;     __device__ __forceinline__ void operator()(const f32x4 (&acc)[2][2][4][2], const Unit& u, int wr, int wc, int fr, int fq) const {
;         const int row0 = u.pm * BM + wr * 64 + fr, col0 = u.pn * 128 + wc * 32 + 8 * fq;
; #pragma unroll
;         for (int ai = 0; ai < 2; ++ai)
; #pragma unroll
;             for (int m = 0; m < 4; ++m) {
;                 const int row = row0 + ai * HALF + m * 16;
;                 const float rs = rsqrtf(ss[row] * (1.f / DM) + EPS);
;                 float h[8];
; #pragma unroll
;                 for (int n = 0; n < 2; ++n)
; #pragma unroll
;                     for (int j = 0; j < 4; ++j) { const float gg = acc[ai][0][m][n][j] * rs, uu = acc[ai][1][m][n][j] * rs; h[4 * n + j] = siluf_(gg) * uu; }
;                 u32x4 w; w.x = cvt_pk(h[0], h[1]); w.y = cvt_pk(h[2], h[3]); w.z = cvt_pk(h[4], h[5]); w.w = cvt_pk(h[6], h[7]);
;                 *(u32x4*)(H + (size_t)row * DFF + col0) = w;
;             }
	v_mul_f32_e32 v61, v61, v180
	v_mul_f32_e32 v57, v57, v180
	v_mul_f32_e32 v62, v62, v180
	v_mul_f32_e32 v58, v58, v180
	v_mul_f32_e32 v63, v63, v180
	v_mul_f32_e32 v59, v59, v180
	v_mul_f32_e32 v52, v52, v180
	v_mul_f32_e32 v48, v48, v180
	v_mul_f32_e32 v53, v53, v180
	v_mul_f32_e32 v49, v49, v180
	v_mul_f32_e32 v54, v54, v180
	v_mul_f32_e32 v50, v50, v180
	v_mul_f32_e32 v55, v55, v180
	v_mul_f32_e32 v51, v51, v180
	v_mul_f32_e32 v172, 0xbfb8aa3b, v60
	v_mul_f32_e32 v173, 0xbfb8aa3b, v61
	v_mul_f32_e32 v174, 0xbfb8aa3b, v62
	v_mul_f32_e32 v175, 0xbfb8aa3b, v63
	v_mul_f32_e32 v176, 0xbfb8aa3b, v52
	v_mul_f32_e32 v177, 0xbfb8aa3b, v53
	v_mul_f32_e32 v178, 0xbfb8aa3b, v54
	v_mul_f32_e32 v179, 0xbfb8aa3b, v55
	v_exp_f32_e32 v172, v172
	v_exp_f32_e32 v173, v173
	v_exp_f32_e32 v174, v174
	v_exp_f32_e32 v175, v175
	v_exp_f32_e32 v176, v176
	v_exp_f32_e32 v177, v177
	v_exp_f32_e32 v178, v178
	v_exp_f32_e32 v179, v179
	v_add_f32_e32 v172, 1.0, v172
	v_add_f32_e32 v173, 1.0, v173
	v_add_f32_e32 v174, 1.0, v174
	v_add_f32_e32 v175, 1.0, v175
	v_add_f32_e32 v176, 1.0, v176
	v_add_f32_e32 v177, 1.0, v177
	v_add_f32_e32 v178, 1.0, v178
	v_add_f32_e32 v179, 1.0, v179
	v_rcp_f32_e32 v172, v172
	v_rcp_f32_e32 v173, v173
	v_rcp_f32_e32 v174, v174
	v_rcp_f32_e32 v175, v175
	v_rcp_f32_e32 v176, v176
	v_rcp_f32_e32 v177, v177
	v_rcp_f32_e32 v178, v178
	v_rcp_f32_e32 v179, v179
	v_mul_f32_e32 v60, v60, v172
	v_mul_f32_e32 v61, v61, v173
	v_mul_f32_e32 v62, v62, v174
	v_mul_f32_e32 v63, v63, v175
	v_mul_f32_e32 v52, v52, v176
	v_mul_f32_e32 v53, v53, v177
	v_mul_f32_e32 v54, v54, v178
	v_mul_f32_e32 v55, v55, v179
	v_mul_f32_e32 v60, v56, v60
	v_mul_f32_e32 v61, v57, v61
	v_mul_f32_e32 v62, v58, v62
	v_mul_f32_e32 v63, v59, v63
	v_mul_f32_e32 v52, v48, v52
	v_mul_f32_e32 v53, v49, v53
	v_mul_f32_e32 v54, v50, v54
	v_mul_f32_e32 v55, v51, v55
	v_mad_i64_i32 v[184:185], s[22:23], v182, s64, v[186:187]
	v_cvt_pk_bf16_f32 v172, v60, v61
	v_cvt_pk_bf16_f32 v173, v62, v63
	v_cvt_pk_bf16_f32 v174, v52, v53
	v_cvt_pk_bf16_f32 v175, v54, v55
	v_lshl_add_u64 v[184:185], v[184:185], 0, v[188:189]
	global_store_dwordx4 v[184:185], v[172:175], off
	v_fmamk_f32 v180, v166, 0x3a800000, v217
	v_cmp_gt_f32_e32 vcc, s15, v180
	v_mul_f32_e32 v181, 0x4b800000, v180
	s_nop 0
	v_cndmask_b32_e32 v180, v180, v181, vcc
	v_rsq_f32_e32 v180, v180
	v_add_u32_e32 v182, 144, v138
	v_mul_f32_e32 v181, 0x45800000, v180
	v_cndmask_b32_e32 v180, v180, v181, vcc
	v_mul_f32_e32 v44, v44, v180
	v_mul_f32_e32 v40, v40, v180
	v_mul_f32_e32 v45, v45, v180
	v_mul_f32_e32 v41, v41, v180
	v_mul_f32_e32 v46, v46, v180
	v_mul_f32_e32 v42, v42, v180
	v_mul_f32_e32 v47, v47, v180
	v_mul_f32_e32 v43, v43, v180
	v_mul_f32_e32 v36, v36, v180
	v_mul_f32_e32 v32, v32, v180
	v_mul_f32_e32 v37, v37, v180
	v_mul_f32_e32 v33, v33, v180
	v_mul_f32_e32 v38, v38, v180
	v_mul_f32_e32 v34, v34, v180
	v_mul_f32_e32 v39, v39, v180
	v_mul_f32_e32 v35, v35, v180
	v_mul_f32_e32 v172, 0xbfb8aa3b, v44
	v_mul_f32_e32 v173, 0xbfb8aa3b, v45
	v_mul_f32_e32 v174, 0xbfb8aa3b, v46
	v_mul_f32_e32 v175, 0xbfb8aa3b, v47
	v_mul_f32_e32 v176, 0xbfb8aa3b, v36
	v_mul_f32_e32 v177, 0xbfb8aa3b, v37
	v_mul_f32_e32 v178, 0xbfb8aa3b, v38
	v_mul_f32_e32 v179, 0xbfb8aa3b, v39
	v_exp_f32_e32 v172, v172
	v_exp_f32_e32 v173, v173
	v_exp_f32_e32 v174, v174
	v_exp_f32_e32 v175, v175
	v_exp_f32_e32 v176, v176
	v_exp_f32_e32 v177, v177
	v_exp_f32_e32 v178, v178
	v_exp_f32_e32 v179, v179
	v_add_f32_e32 v172, 1.0, v172
	v_add_f32_e32 v173, 1.0, v173
	v_add_f32_e32 v174, 1.0, v174
	v_add_f32_e32 v175, 1.0, v175
	v_add_f32_e32 v176, 1.0, v176
	v_add_f32_e32 v177, 1.0, v177
	v_add_f32_e32 v178, 1.0, v178
	v_add_f32_e32 v179, 1.0, v179
	v_rcp_f32_e32 v172, v172
	v_rcp_f32_e32 v173, v173
	v_rcp_f32_e32 v174, v174
	v_rcp_f32_e32 v175, v175
	v_rcp_f32_e32 v176, v176
	v_rcp_f32_e32 v177, v177
	v_rcp_f32_e32 v178, v178
	v_rcp_f32_e32 v179, v179
	v_mul_f32_e32 v44, v44, v172
	v_mul_f32_e32 v45, v45, v173
	v_mul_f32_e32 v46, v46, v174
	v_mul_f32_e32 v47, v47, v175
	v_mul_f32_e32 v36, v36, v176
	v_mul_f32_e32 v37, v37, v177
	v_mul_f32_e32 v38, v38, v178
	v_mul_f32_e32 v39, v39, v179
	v_mul_f32_e32 v44, v40, v44
	v_mul_f32_e32 v45, v41, v45
	v_mul_f32_e32 v46, v42, v46
	v_mul_f32_e32 v47, v43, v47
	v_mul_f32_e32 v36, v32, v36
	v_mul_f32_e32 v37, v33, v37
	v_mul_f32_e32 v38, v34, v38
	v_mul_f32_e32 v39, v35, v39
	v_mad_i64_i32 v[184:185], s[22:23], v182, s64, v[186:187]
	v_cvt_pk_bf16_f32 v172, v44, v45
	v_cvt_pk_bf16_f32 v173, v46, v47
	v_cvt_pk_bf16_f32 v174, v36, v37
	v_cvt_pk_bf16_f32 v175, v38, v39
	v_lshl_add_u64 v[184:185], v[184:185], 0, v[188:189]
	global_store_dwordx4 v[184:185], v[172:175], off
	v_fmamk_f32 v180, v167, 0x3a800000, v217
	v_cmp_gt_f32_e32 vcc, s15, v180
	v_mul_f32_e32 v181, 0x4b800000, v180
	s_nop 0
	v_cndmask_b32_e32 v180, v180, v181, vcc
	v_rsq_f32_e32 v180, v180
	v_add_u32_e32 v182, 160, v138
	v_mul_f32_e32 v181, 0x45800000, v180
; DI unsigned cvt_pk(float lo, float hi) { unsigned r; asm("v_cvt_pk_bf16_f32 %0, %1, %2" : "=v"(r) : "v"(lo), "v"(hi)); return r; }
; DI float siluf_(float x) { return x * sigmoidf_(x); }
;     __device__ __forceinline__ void operator()(const f32x4 (&acc)[2][2][4][2], const Unit& u, int wr, int wc, int fr, int fq) const {
;         const int row0 = u.pm * BM + wr * 64 + fr, col0 = u.pn * 128 + wc * 32 + 8 * fq;
; #pragma unroll
;         for (int ai = 0; ai < 2; ++ai)
; #pragma unroll
;             for (int m = 0; m < 4; ++m) {
;                 const int row = row0 + ai * HALF + m * 16;
;                 const float rs = rsqrtf(ss[row] * (1.f / DM) + EPS);
;                 float h[8];
; #pragma unroll
;                 for (int n = 0; n < 2; ++n)
; #pragma unroll
;                     for (int j = 0; j < 4; ++j) { const float gg = acc[ai][0][m][n][j] * rs, uu = acc[ai][1][m][n][j] * rs; h[4 * n + j] = siluf_(gg) * uu; }
;                 u32x4 w; w.x = cvt_pk(h[0], h[1]); w.y = cvt_pk(h[2], h[3]); w.z = cvt_pk(h[4], h[5]); w.w = cvt_pk(h[6], h[7]);
;                 *(u32x4*)(H + (size_t)row * DFF + col0) = w;
;             }
	v_cndmask_b32_e32 v180, v180, v181, vcc
	v_mul_f32_e32 v28, v28, v180
	v_mul_f32_e32 v24, v24, v180
	v_mul_f32_e32 v29, v29, v180
	v_mul_f32_e32 v25, v25, v180
	v_mul_f32_e32 v30, v30, v180
	v_mul_f32_e32 v26, v26, v180
	v_mul_f32_e32 v31, v31, v180
	v_mul_f32_e32 v27, v27, v180
	v_mul_f32_e32 v20, v20, v180
	v_mul_f32_e32 v16, v16, v180
	v_mul_f32_e32 v21, v21, v180
	v_mul_f32_e32 v17, v17, v180
	v_mul_f32_e32 v22, v22, v180
	v_mul_f32_e32 v18, v18, v180
	v_mul_f32_e32 v23, v23, v180
	v_mul_f32_e32 v19, v19, v180
	v_mul_f32_e32 v172, 0xbfb8aa3b, v28
	v_mul_f32_e32 v173, 0xbfb8aa3b, v29
	v_mul_f32_e32 v174, 0xbfb8aa3b, v30
	v_mul_f32_e32 v175, 0xbfb8aa3b, v31
	v_mul_f32_e32 v176, 0xbfb8aa3b, v20
	v_mul_f32_e32 v177, 0xbfb8aa3b, v21
	v_mul_f32_e32 v178, 0xbfb8aa3b, v22
	v_mul_f32_e32 v179, 0xbfb8aa3b, v23
	v_exp_f32_e32 v172, v172
	v_exp_f32_e32 v173, v173
	v_exp_f32_e32 v174, v174
	v_exp_f32_e32 v175, v175
	v_exp_f32_e32 v176, v176
	v_exp_f32_e32 v177, v177
	v_exp_f32_e32 v178, v178
	v_exp_f32_e32 v179, v179
	v_add_f32_e32 v172, 1.0, v172
	v_add_f32_e32 v173, 1.0, v173
	v_add_f32_e32 v174, 1.0, v174
	v_add_f32_e32 v175, 1.0, v175
	v_add_f32_e32 v176, 1.0, v176
	v_add_f32_e32 v177, 1.0, v177
	v_add_f32_e32 v178, 1.0, v178
	v_add_f32_e32 v179, 1.0, v179
	v_rcp_f32_e32 v172, v172
	v_rcp_f32_e32 v173, v173
	v_rcp_f32_e32 v174, v174
	v_rcp_f32_e32 v175, v175
	v_rcp_f32_e32 v176, v176
	v_rcp_f32_e32 v177, v177
	v_rcp_f32_e32 v178, v178
	v_rcp_f32_e32 v179, v179
	v_mul_f32_e32 v28, v28, v172
	v_mul_f32_e32 v29, v29, v173
	v_mul_f32_e32 v30, v30, v174
	v_mul_f32_e32 v31, v31, v175
	v_mul_f32_e32 v20, v20, v176
	v_mul_f32_e32 v21, v21, v177
	v_mul_f32_e32 v22, v22, v178
	v_mul_f32_e32 v23, v23, v179
	v_mul_f32_e32 v28, v24, v28
	v_mul_f32_e32 v29, v25, v29
	v_mul_f32_e32 v30, v26, v30
	v_mul_f32_e32 v31, v27, v31
	v_mul_f32_e32 v20, v16, v20
	v_mul_f32_e32 v21, v17, v21
	v_mul_f32_e32 v22, v18, v22
	v_mul_f32_e32 v23, v19, v23
	v_mad_i64_i32 v[184:185], s[22:23], v182, s64, v[186:187]
	v_cvt_pk_bf16_f32 v172, v28, v29
	v_cvt_pk_bf16_f32 v173, v30, v31
	v_cvt_pk_bf16_f32 v174, v20, v21
	v_cvt_pk_bf16_f32 v175, v22, v23
	v_lshl_add_u64 v[184:185], v[184:185], 0, v[188:189]
	global_store_dwordx4 v[184:185], v[172:175], off
	v_fmamk_f32 v180, v168, 0x3a800000, v217
	v_cmp_gt_f32_e32 vcc, s15, v180
	v_mul_f32_e32 v181, 0x4b800000, v180
	s_nop 0
	v_cndmask_b32_e32 v180, v180, v181, vcc
	v_rsq_f32_e32 v180, v180
	v_add_u32_e32 v182, 176, v138
	v_mul_f32_e32 v181, 0x45800000, v180
	v_cndmask_b32_e32 v180, v180, v181, vcc
	v_mul_f32_e32 v12, v12, v180
	v_mul_f32_e32 v8, v8, v180
	v_mul_f32_e32 v13, v13, v180
	v_mul_f32_e32 v9, v9, v180
	v_mul_f32_e32 v14, v14, v180
	v_mul_f32_e32 v10, v10, v180
	v_mul_f32_e32 v15, v15, v180
	v_mul_f32_e32 v11, v11, v180
	v_mul_f32_e32 v4, v4, v180
	v_mul_f32_e32 v0, v0, v180
	v_mul_f32_e32 v5, v5, v180
	v_mul_f32_e32 v1, v1, v180
	v_mul_f32_e32 v6, v6, v180
	v_mul_f32_e32 v2, v2, v180
	v_mul_f32_e32 v7, v7, v180
	v_mul_f32_e32 v3, v3, v180
	v_mul_f32_e32 v172, 0xbfb8aa3b, v12
	v_mul_f32_e32 v173, 0xbfb8aa3b, v13
	v_mul_f32_e32 v174, 0xbfb8aa3b, v14
	v_mul_f32_e32 v175, 0xbfb8aa3b, v15
	v_mul_f32_e32 v176, 0xbfb8aa3b, v4
	v_mul_f32_e32 v177, 0xbfb8aa3b, v5
	v_mul_f32_e32 v178, 0xbfb8aa3b, v6
	v_mul_f32_e32 v179, 0xbfb8aa3b, v7
	v_exp_f32_e32 v172, v172
	v_exp_f32_e32 v173, v173
	v_exp_f32_e32 v174, v174
	v_exp_f32_e32 v175, v175
	v_exp_f32_e32 v176, v176
	v_exp_f32_e32 v177, v177
	v_exp_f32_e32 v178, v178
	v_exp_f32_e32 v179, v179
	v_add_f32_e32 v172, 1.0, v172
	v_add_f32_e32 v173, 1.0, v173
	v_add_f32_e32 v174, 1.0, v174
	v_add_f32_e32 v175, 1.0, v175
	v_add_f32_e32 v176, 1.0, v176
	v_add_f32_e32 v177, 1.0, v177
	v_add_f32_e32 v178, 1.0, v178
	v_add_f32_e32 v179, 1.0, v179
	v_rcp_f32_e32 v172, v172
	v_rcp_f32_e32 v173, v173
	v_rcp_f32_e32 v174, v174
	v_rcp_f32_e32 v175, v175
	v_rcp_f32_e32 v176, v176
	v_rcp_f32_e32 v177, v177
	v_rcp_f32_e32 v178, v178
	v_rcp_f32_e32 v179, v179
	v_mul_f32_e32 v12, v12, v172
	v_mul_f32_e32 v13, v13, v173
	v_mul_f32_e32 v14, v14, v174
	v_mul_f32_e32 v15, v15, v175
	v_mul_f32_e32 v4, v4, v176
	v_mul_f32_e32 v5, v5, v177
	v_mul_f32_e32 v6, v6, v178
	v_mul_f32_e32 v7, v7, v179
	v_mul_f32_e32 v12, v8, v12
	v_mul_f32_e32 v13, v9, v13
	v_mul_f32_e32 v14, v10, v14
	v_mul_f32_e32 v15, v11, v15
	v_mul_f32_e32 v4, v0, v4
	v_mul_f32_e32 v5, v1, v5
	v_mul_f32_e32 v6, v2, v6
	v_mul_f32_e32 v7, v3, v7
	v_mad_i64_i32 v[184:185], s[22:23], v182, s64, v[186:187]
	v_cvt_pk_bf16_f32 v172, v12, v13
	v_cvt_pk_bf16_f32 v173, v14, v15
	v_cvt_pk_bf16_f32 v174, v4, v5
	v_cvt_pk_bf16_f32 v175, v6, v7
	v_lshl_add_u64 v[184:185], v[184:185], 0, v[188:189]
	global_store_dwordx4 v[184:185], v[172:175], off
	s_mov_b64 s[22:23], -1
	s_andn2_b64 vcc, exec, s[6:7]
	s_cbranch_vccnz .LBB0_1287
	s_andn2_b64 vcc, exec, s[2:3]
	s_cbranch_vccnz .LBB0_1286
	s_barrier
	s_branch .LBB0_1286
